# same as previous plus one explicit wait state before a readfirstlane in the prep row loop
# speedup vs baseline: 1.0013x; 1.0013x over previous
; __device__ __forceinline__ unsigned pk2(float lo, float hi) { const f32x2_t f = {lo, hi}; const bf16x2_t b = __builtin_convertvector(f, bf16x2_t); return __builtin_bit_cast(unsigned, b); }
; __device__ __forceinline__ void phase_prep(const Params& P, LAS unsigned char* lds) {
;     ...
;     for (int chunk = bid; chunk < TALL / 32; chunk += G) {
; #pragma unroll 1
;       for (int rr = 0; rr < 4; ++rr) {
;         const int row = chunk * 32 + wave * 4 + rr;
;         const float* src = row < 65536 ? P.in[I_XP] + (size_t)row * DM : P.in[I_XS] + (size_t)(row - 65536) * DM;
;         f32x4 v[4]; float s = 0.f;
; #pragma unroll
;         for (int j = 0; j < 4; ++j) { v[j] = *(const f32x4*)(src + 4 * lane + 256 * j); s += v[j][0] * v[j][0] + v[j][1] * v[j][1] + v[j][2] * v[j][2] + v[j][3] * v[j][3]; }
; #pragma unroll
;         for (int o = 1; o < 64; o <<= 1) s += __shfl_xor(s, o);
; #pragma unroll
;         for (int j = 0; j < 4; ++j) { u32x2 o; o.x = pk2(v[j][0], v[j][1]); o.y = pk2(v[j][2], v[j][3]); *(u32x2*)(xb + (size_t)row * DM + 4 * lane + 256 * j) = o; }
;         if (lane == 0) rstd1[row] = rsqrtf(s * (1.0f / 1024.0f) + 1e-6f);
;       }
.LBB0_935:
	s_nop 0
	v_readfirstlane_b32 s0, v4
	v_readlane_b32 s10, v253, 16
	v_readlane_b32 s11, v253, 17
	s_nop 0
	s_cmp_gt_u32 s0, 0xffff
	s_cselect_b32 s10, s10, s36
	s_cselect_b32 s11, s11, s37
	v_mov_b32_e32 v8, v4
	v_ashrrev_i32_e32 v9, 31, v4
	v_lshlrev_b64 v[10:11], 12, v[8:9]
	v_lshl_add_u64 v[10:11], s[10:11], 0, v[10:11]
	v_lshl_add_u64 v[10:11], v[10:11], 0, v[80:81]
	v_mov_b32_e32 v98, 0x1000
	v_mov_b32_e32 v99, 0
	v_lshl_add_u64 v[92:93], v[98:99], 0, v[10:11]
	v_lshl_add_u64 v[94:95], v[98:99], 0, v[92:93]
	v_lshl_add_u64 v[96:97], v[98:99], 0, v[94:95]
	global_load_dwordx4 v[100:103], v[10:11], off
	global_load_dwordx4 v[104:107], v[10:11], off offset:1024
	global_load_dwordx4 v[108:111], v[10:11], off offset:2048
	global_load_dwordx4 v[112:115], v[10:11], off offset:3072
	global_load_dwordx4 v[116:119], v[92:93], off
	global_load_dwordx4 v[120:123], v[92:93], off offset:1024
	global_load_dwordx4 v[124:127], v[92:93], off offset:2048
	global_load_dwordx4 v[128:131], v[92:93], off offset:3072
	global_load_dwordx4 v[132:135], v[94:95], off
	global_load_dwordx4 v[136:139], v[94:95], off offset:1024
	global_load_dwordx4 v[140:143], v[94:95], off offset:2048
	global_load_dwordx4 v[144:147], v[94:95], off offset:3072
	global_load_dwordx4 v[148:151], v[96:97], off
	global_load_dwordx4 v[152:155], v[96:97], off offset:1024
	global_load_dwordx4 v[156:159], v[96:97], off offset:2048
	global_load_dwordx4 v[160:163], v[96:97], off offset:3072
	s_waitcnt vmcnt(12)
	v_mul_f32_e32 v164, v101, v101
	v_mul_f32_e32 v168, v105, v105
	v_mul_f32_e32 v172, v109, v109
	v_fmac_f32_e32 v164, v100, v100
	v_fmac_f32_e32 v168, v104, v104
	v_mul_f32_e32 v176, v113, v113
	v_fmac_f32_e32 v172, v108, v108
	v_fmac_f32_e32 v164, v102, v102
	v_fmac_f32_e32 v168, v106, v106
	v_fmac_f32_e32 v176, v112, v112
	v_fmac_f32_e32 v172, v110, v110
	v_fmac_f32_e32 v164, v103, v103
	v_fmac_f32_e32 v168, v107, v107
	v_fmac_f32_e32 v176, v114, v114
	v_fmac_f32_e32 v172, v111, v111
	v_add_f32_e32 v164, v164, v168
	v_fmac_f32_e32 v176, v115, v115
	v_add_f32_e32 v164, v164, v172
	v_add_f32_e32 v164, v164, v176
	s_waitcnt vmcnt(8)
	v_mul_f32_e32 v165, v117, v117
	v_mul_f32_e32 v169, v121, v121
	v_mul_f32_e32 v173, v125, v125
	v_fmac_f32_e32 v165, v116, v116
	v_fmac_f32_e32 v169, v120, v120
	v_mul_f32_e32 v177, v129, v129
	v_fmac_f32_e32 v173, v124, v124
	v_fmac_f32_e32 v165, v118, v118
	v_fmac_f32_e32 v169, v122, v122
	v_fmac_f32_e32 v177, v128, v128
	v_fmac_f32_e32 v173, v126, v126
	v_fmac_f32_e32 v165, v119, v119
	v_fmac_f32_e32 v169, v123, v123
	v_fmac_f32_e32 v177, v130, v130
	v_fmac_f32_e32 v173, v127, v127
	v_add_f32_e32 v165, v165, v169
	v_fmac_f32_e32 v177, v131, v131
	v_add_f32_e32 v165, v165, v173
	v_add_f32_e32 v165, v165, v177
	s_waitcnt vmcnt(4)
	v_mul_f32_e32 v166, v133, v133
	v_mul_f32_e32 v170, v137, v137
	v_mul_f32_e32 v174, v141, v141
	v_fmac_f32_e32 v166, v132, v132
	v_fmac_f32_e32 v170, v136, v136
	v_mul_f32_e32 v178, v145, v145
	v_fmac_f32_e32 v174, v140, v140
	v_fmac_f32_e32 v166, v134, v134
	v_fmac_f32_e32 v170, v138, v138
	v_fmac_f32_e32 v178, v144, v144
	v_fmac_f32_e32 v174, v142, v142
	v_fmac_f32_e32 v166, v135, v135
	v_fmac_f32_e32 v170, v139, v139
	v_fmac_f32_e32 v178, v146, v146
	v_fmac_f32_e32 v174, v143, v143
	v_add_f32_e32 v166, v166, v170
	v_fmac_f32_e32 v178, v147, v147
	v_add_f32_e32 v166, v166, v174
	v_add_f32_e32 v166, v166, v178
	s_waitcnt vmcnt(0)
	v_mul_f32_e32 v167, v149, v149
	v_mul_f32_e32 v171, v153, v153
	v_mul_f32_e32 v175, v157, v157
	v_fmac_f32_e32 v167, v148, v148
	v_fmac_f32_e32 v171, v152, v152
	v_mul_f32_e32 v179, v161, v161
	v_fmac_f32_e32 v175, v156, v156
	v_fmac_f32_e32 v167, v150, v150
	v_fmac_f32_e32 v171, v154, v154
	v_fmac_f32_e32 v179, v160, v160
	v_fmac_f32_e32 v175, v158, v158
	v_fmac_f32_e32 v167, v151, v151
	v_fmac_f32_e32 v171, v155, v155
	v_fmac_f32_e32 v179, v162, v162
	v_fmac_f32_e32 v175, v159, v159
	v_add_f32_e32 v167, v167, v171
	v_fmac_f32_e32 v179, v163, v163
	v_add_f32_e32 v167, v167, v175
	v_add_f32_e32 v167, v167, v179
	ds_bpermute_b32 v180, v16, v164
	ds_bpermute_b32 v181, v16, v165
	ds_bpermute_b32 v182, v16, v166
	ds_bpermute_b32 v183, v16, v167
	s_waitcnt lgkmcnt(0)
	v_add_f32_e32 v164, v164, v180
	v_add_f32_e32 v165, v165, v181
	v_add_f32_e32 v166, v166, v182
	v_add_f32_e32 v167, v167, v183
	ds_bpermute_b32 v180, v17, v164
	ds_bpermute_b32 v181, v17, v165
	ds_bpermute_b32 v182, v17, v166
	ds_bpermute_b32 v183, v17, v167
	s_waitcnt lgkmcnt(0)
	v_add_f32_e32 v164, v164, v180
	v_add_f32_e32 v165, v165, v181
	v_add_f32_e32 v166, v166, v182
	v_add_f32_e32 v167, v167, v183
	ds_bpermute_b32 v180, v18, v164
	ds_bpermute_b32 v181, v18, v165
	ds_bpermute_b32 v182, v18, v166
	ds_bpermute_b32 v183, v18, v167
	s_waitcnt lgkmcnt(0)
; __device__ __forceinline__ unsigned pk2(float lo, float hi) { const f32x2_t f = {lo, hi}; const bf16x2_t b = __builtin_convertvector(f, bf16x2_t); return __builtin_bit_cast(unsigned, b); }
; __device__ __forceinline__ void phase_prep(const Params& P, LAS unsigned char* lds) {
;     ...
;         for (int o = 1; o < 64; o <<= 1) s += __shfl_xor(s, o);
; #pragma unroll
;         for (int j = 0; j < 4; ++j) { u32x2 o; o.x = pk2(v[j][0], v[j][1]); o.y = pk2(v[j][2], v[j][3]); *(u32x2*)(xb + (size_t)row * DM + 4 * lane + 256 * j) = o; }
;         if (lane == 0) rstd1[row] = rsqrtf(s * (1.0f / 1024.0f) + 1e-6f);
;       }
	v_add_f32_e32 v164, v164, v180
	v_add_f32_e32 v165, v165, v181
	v_add_f32_e32 v166, v166, v182
	v_add_f32_e32 v167, v167, v183
	ds_bpermute_b32 v180, v19, v164
	ds_bpermute_b32 v181, v19, v165
	ds_bpermute_b32 v182, v19, v166
	ds_bpermute_b32 v183, v19, v167
	s_waitcnt lgkmcnt(0)
	v_add_f32_e32 v164, v164, v180
	v_add_f32_e32 v165, v165, v181
	v_add_f32_e32 v166, v166, v182
	v_add_f32_e32 v167, v167, v183
	ds_bpermute_b32 v180, v20, v164
	ds_bpermute_b32 v181, v20, v165
	ds_bpermute_b32 v182, v20, v166
	ds_bpermute_b32 v183, v20, v167
	s_waitcnt lgkmcnt(0)
	v_add_f32_e32 v164, v164, v180
	v_add_f32_e32 v165, v165, v181
	v_add_f32_e32 v166, v166, v182
	v_add_f32_e32 v167, v167, v183
	ds_bpermute_b32 v180, v21, v164
	ds_bpermute_b32 v181, v21, v165
	ds_bpermute_b32 v182, v21, v166
	ds_bpermute_b32 v183, v21, v167
	s_waitcnt lgkmcnt(0)
	v_add_f32_e32 v164, v164, v180
	v_add_f32_e32 v165, v165, v181
	v_add_f32_e32 v166, v166, v182
	v_add_f32_e32 v167, v167, v183
	v_lshlrev_b64 v[12:13], 11, v[8:9]
	v_lshl_add_u64 v[40:41], v[2:3], 0, v[12:13]
	v_lshl_add_u64 v[42:43], v[98:99], 0, v[40:41]
	v_cvt_pk_bf16_f32 v184, v100, v101
	v_cvt_pk_bf16_f32 v185, v102, v103
	v_cvt_pk_bf16_f32 v186, v104, v105
	v_cvt_pk_bf16_f32 v187, v106, v107
	v_cvt_pk_bf16_f32 v188, v108, v109
	v_cvt_pk_bf16_f32 v189, v110, v111
	v_cvt_pk_bf16_f32 v190, v112, v113
	v_cvt_pk_bf16_f32 v191, v114, v115
	v_cvt_pk_bf16_f32 v192, v116, v117
	v_cvt_pk_bf16_f32 v193, v118, v119
	v_cvt_pk_bf16_f32 v194, v120, v121
	v_cvt_pk_bf16_f32 v195, v122, v123
	v_cvt_pk_bf16_f32 v196, v124, v125
	v_cvt_pk_bf16_f32 v197, v126, v127
	v_cvt_pk_bf16_f32 v198, v128, v129
	v_cvt_pk_bf16_f32 v199, v130, v131
	v_cvt_pk_bf16_f32 v200, v132, v133
	v_cvt_pk_bf16_f32 v201, v134, v135
	v_cvt_pk_bf16_f32 v202, v136, v137
	v_cvt_pk_bf16_f32 v203, v138, v139
	v_cvt_pk_bf16_f32 v204, v140, v141
	v_cvt_pk_bf16_f32 v205, v142, v143
	v_cvt_pk_bf16_f32 v206, v144, v145
	v_cvt_pk_bf16_f32 v207, v146, v147
	v_cvt_pk_bf16_f32 v84, v148, v149
	v_cvt_pk_bf16_f32 v85, v150, v151
	v_cvt_pk_bf16_f32 v86, v152, v153
	v_cvt_pk_bf16_f32 v87, v154, v155
	v_cvt_pk_bf16_f32 v88, v156, v157
	v_cvt_pk_bf16_f32 v89, v158, v159
	v_cvt_pk_bf16_f32 v90, v160, v161
	v_cvt_pk_bf16_f32 v91, v162, v163
	flat_store_dwordx2 v[40:41], v[184:185]
	flat_store_dwordx2 v[40:41], v[186:187] offset:512
	flat_store_dwordx2 v[40:41], v[188:189] offset:1024
	flat_store_dwordx2 v[40:41], v[190:191] offset:1536
	flat_store_dwordx2 v[40:41], v[192:193] offset:2048
	flat_store_dwordx2 v[40:41], v[194:195] offset:2560
	flat_store_dwordx2 v[40:41], v[196:197] offset:3072
	flat_store_dwordx2 v[40:41], v[198:199] offset:3584
	flat_store_dwordx2 v[42:43], v[200:201]
	flat_store_dwordx2 v[42:43], v[202:203] offset:512
	flat_store_dwordx2 v[42:43], v[204:205] offset:1024
	flat_store_dwordx2 v[42:43], v[206:207] offset:1536
	flat_store_dwordx2 v[42:43], v[84:85] offset:2048
	flat_store_dwordx2 v[42:43], v[86:87] offset:2560
	flat_store_dwordx2 v[42:43], v[88:89] offset:3072
	flat_store_dwordx2 v[42:43], v[90:91] offset:3584
	s_and_saveexec_b64 s[10:11], vcc
	v_lshl_add_u64 v[12:13], v[8:9], 2, s[6:7]
	v_fmamk_f32 v164, v164, 0x3a800000, v218
	v_mul_f32_e32 v180, 0x4b800000, v164
	v_cmp_gt_f32_e64 s[0:1], s71, v164
	s_nop 1
	v_cndmask_b32_e64 v164, v164, v180, s[0:1]
	v_rsq_f32_e32 v164, v164
	s_nop 0
	v_mul_f32_e32 v180, 0x45800000, v164
	v_cndmask_b32_e64 v164, v164, v180, s[0:1]
	flat_store_dword v[12:13], v164
	v_fmamk_f32 v165, v165, 0x3a800000, v218
	v_mul_f32_e32 v181, 0x4b800000, v165
	v_cmp_gt_f32_e64 s[0:1], s71, v165
	s_nop 1
	v_cndmask_b32_e64 v165, v165, v181, s[0:1]
	v_rsq_f32_e32 v165, v165
	s_nop 0
	v_mul_f32_e32 v181, 0x45800000, v165
	v_cndmask_b32_e64 v165, v165, v181, s[0:1]
	flat_store_dword v[12:13], v165 offset:4
	v_fmamk_f32 v166, v166, 0x3a800000, v218
	v_mul_f32_e32 v182, 0x4b800000, v166
	v_cmp_gt_f32_e64 s[0:1], s71, v166
	s_nop 1
	v_cndmask_b32_e64 v166, v166, v182, s[0:1]
	v_rsq_f32_e32 v166, v166
	s_nop 0
	v_mul_f32_e32 v182, 0x45800000, v166
	v_cndmask_b32_e64 v166, v166, v182, s[0:1]
	flat_store_dword v[12:13], v166 offset:8
	v_fmamk_f32 v167, v167, 0x3a800000, v218
	v_mul_f32_e32 v183, 0x4b800000, v167
	v_cmp_gt_f32_e64 s[0:1], s71, v167
	s_nop 1
	v_cndmask_b32_e64 v167, v167, v183, s[0:1]
	v_rsq_f32_e32 v167, v167
	s_nop 0
	v_mul_f32_e32 v183, 0x45800000, v167
	v_cndmask_b32_e64 v167, v167, v183, s[0:1]
	flat_store_dword v[12:13], v167 offset:12
	s_or_b64 exec, exec, s[10:11]
	s_branch .LBB0_934
